# best_b + P4 row loop: in-body waits cover only older ops, the next-row prefetch is waited for at the loop end
# baseline (speedup 1.0000x reference)
.LBB0_401:
	s_or_b64 exec, exec, s[36:37]
	s_waitcnt vmcnt(4)
	s_waitcnt lgkmcnt(2)
	v_mov_b64_e32 v[162:163], v[146:147]
	s_waitcnt lgkmcnt(0)
	v_mov_b64_e32 v[166:167], v[150:151]
	v_mov_b64_e32 v[170:171], v[154:155]
	v_mov_b64_e32 v[174:175], v[158:159]
	v_lshl_add_u64 v[188:189], v[188:189], 0, s[100:101]
	v_lshl_add_u64 v[186:187], v[186:187], 0, s[28:29]
	s_and_b64 vcc, exec, s[34:35]
	v_mov_b64_e32 v[160:161], v[144:145]
	v_mov_b64_e32 v[164:165], v[148:149]
	v_mov_b64_e32 v[168:169], v[152:153]
	v_mov_b64_e32 v[172:173], v[156:157]
	s_cbranch_vccnz .LBB0_399

.LBB0_404:
	v_mul_f32_e32 v206, v173, v173
	v_mul_f32_e32 v207, v175, v175
	v_fmac_f32_e32 v206, v172, v172
	v_fmac_f32_e32 v207, v174, v174
	v_add_f32_e32 v206, v206, v207
	v_mul_f32_e32 v207, v169, v169
	v_mul_f32_e32 v223, v171, v171
	v_fmac_f32_e32 v207, v168, v168
	v_fmac_f32_e32 v223, v170, v170
	v_add_f32_e32 v207, v207, v223
	v_add_f32_e32 v206, v207, v206
	v_mul_f32_e32 v207, v165, v165
	v_mul_f32_e32 v223, v167, v167
	v_fmac_f32_e32 v207, v164, v164
	v_fmac_f32_e32 v223, v166, v166
	v_add_f32_e32 v207, v207, v223
	v_add_f32_e32 v206, v207, v206
	v_mul_f32_e32 v207, v161, v161
	v_mul_f32_e32 v223, v163, v163
	v_fmac_f32_e32 v207, v160, v160
	v_fmac_f32_e32 v223, v162, v162
	v_add_f32_e32 v207, v207, v223
	v_add_f32_e32 v206, v207, v206
	ds_bpermute_b32 v207, v209, v206
	s_waitcnt lgkmcnt(0)
	v_add_f32_e32 v206, v206, v207
	ds_bpermute_b32 v207, v211, v206
	s_waitcnt lgkmcnt(0)
	v_add_f32_e32 v206, v206, v207
	ds_bpermute_b32 v207, v212, v206
	s_waitcnt lgkmcnt(0)
	v_add_f32_e32 v206, v206, v207
	ds_bpermute_b32 v207, v213, v206
	s_waitcnt lgkmcnt(0)
	v_add_f32_e32 v206, v206, v207
	ds_bpermute_b32 v207, v214, v206
	s_waitcnt lgkmcnt(0)
	v_add_f32_e32 v206, v206, v207
	ds_bpermute_b32 v207, v215, v206
	s_waitcnt lgkmcnt(0)
	v_add_f32_e32 v206, v206, v207
	v_fmamk_f32 v206, v206, 0x3a800000, v220
	v_mul_f32_e32 v207, 0x4f800000, v206
	v_cmp_gt_f32_e32 vcc, s25, v206
	s_nop 1
	v_cndmask_b32_e32 v206, v206, v207, vcc
	v_sqrt_f32_e32 v207, v206
	s_nop 0
	v_add_u32_e32 v223, -1, v207
	v_add_u32_e32 v224, 1, v207
	v_fma_f32 v225, -v223, v207, v206
	v_fma_f32 v226, -v224, v207, v206
	v_cmp_ge_f32_e64 s[0:1], 0, v225
	s_nop 1
	v_cndmask_b32_e64 v207, v207, v223, s[0:1]
	v_cmp_lt_f32_e64 s[0:1], 0, v226
	s_nop 1
	v_cndmask_b32_e64 v207, v207, v224, s[0:1]
	v_mul_f32_e32 v223, 0x37800000, v207
	v_cndmask_b32_e32 v207, v207, v223, vcc
	v_cmp_class_f32_e32 vcc, v206, v221
	s_nop 1
	v_cndmask_b32_e32 v206, v207, v206, vcc
	v_div_scale_f32 v207, s[0:1], v206, v206, 1.0
	v_rcp_f32_e32 v223, v207
	v_div_scale_f32 v224, vcc, 1.0, v206, 1.0
	v_fma_f32 v225, -v207, v223, 1.0
	v_fmac_f32_e32 v223, v225, v223
	v_mul_f32_e32 v225, v224, v223
	v_fma_f32 v226, -v207, v225, v224
	v_fmac_f32_e32 v225, v226, v223
	v_fma_f32 v207, -v207, v225, v224
	v_div_fmas_f32 v207, v207, v223, v225
	v_div_fixup_f32 v206, v207, v206, 1.0
	v_pk_mul_f32 v[224:225], v[172:173], v[206:207] op_sel_hi:[1,0]
	v_pk_mul_f32 v[172:173], v[174:175], v[206:207] op_sel_hi:[1,0]
	v_pk_fma_f32 v[174:175], v[192:193], v[224:225], v[128:129]
	v_pk_fma_f32 v[172:173], v[190:191], v[172:173], v[130:131]
	v_bfe_u32 v207, v174, 16, 1
	v_bfe_u32 v223, v175, 16, 1
	v_add3_u32 v207, v174, v207, s42
	v_lshrrev_b32_e32 v207, 16, v207
	v_add3_u32 v223, v175, v223, s42
	v_and_or_b32 v224, v223, s43, v207
	v_bfe_u32 v207, v172, 16, 1
	v_add3_u32 v207, v172, v207, s42
	v_bfe_u32 v223, v173, 16, 1
	v_lshrrev_b32_e32 v207, 16, v207
	v_add3_u32 v223, v173, v223, s42
	v_and_or_b32 v225, v223, s43, v207
	global_store_dwordx2 v[186:187], v[224:225], off offset:-1024
	v_pk_mul_f32 v[224:225], v[168:169], v[206:207] op_sel_hi:[1,0]
	v_pk_mul_f32 v[168:169], v[170:171], v[206:207] op_sel_hi:[1,0]
	v_pk_fma_f32 v[170:171], v[196:197], v[224:225], v[132:133]
	v_pk_fma_f32 v[168:169], v[194:195], v[168:169], v[134:135]
	v_bfe_u32 v207, v170, 16, 1
	v_add3_u32 v207, v170, v207, s42
	v_bfe_u32 v223, v171, 16, 1
	v_lshrrev_b32_e32 v207, 16, v207
	v_add3_u32 v223, v171, v223, s42
	v_and_or_b32 v224, v223, s43, v207
	v_bfe_u32 v207, v168, 16, 1
	v_add3_u32 v207, v168, v207, s42
	v_bfe_u32 v223, v169, 16, 1
	v_lshrrev_b32_e32 v207, 16, v207
	v_add3_u32 v223, v169, v223, s42
	v_and_or_b32 v225, v223, s43, v207
	global_store_dwordx2 v[186:187], v[224:225], off offset:-512
	v_pk_mul_f32 v[224:225], v[164:165], v[206:207] op_sel_hi:[1,0]
	v_pk_mul_f32 v[164:165], v[166:167], v[206:207] op_sel_hi:[1,0]
	s_waitcnt vmcnt(6)
	v_pk_fma_f32 v[166:167], v[200:201], v[224:225], v[136:137]
	v_pk_fma_f32 v[164:165], v[198:199], v[164:165], v[138:139]
	v_bfe_u32 v207, v166, 16, 1
	v_add3_u32 v207, v166, v207, s42
	v_bfe_u32 v223, v167, 16, 1
	v_lshrrev_b32_e32 v207, 16, v207
	v_add3_u32 v223, v167, v223, s42
	v_and_or_b32 v224, v223, s43, v207
	v_bfe_u32 v207, v164, 16, 1
	v_add3_u32 v207, v164, v207, s42
	v_bfe_u32 v223, v165, 16, 1
	v_lshrrev_b32_e32 v207, 16, v207
	v_add3_u32 v223, v165, v223, s42
	v_and_or_b32 v225, v223, s43, v207
	v_pk_mul_f32 v[226:227], v[160:161], v[206:207] op_sel_hi:[1,0]
	v_pk_mul_f32 v[160:161], v[162:163], v[206:207] op_sel_hi:[1,0]
	v_mul_f32_e32 v206, v1, v175
	v_mul_f32_e32 v207, v3, v173
	v_fmac_f32_e32 v206, v0, v174
	v_fmac_f32_e32 v207, v2, v172
	v_add_f32_e32 v206, v206, v207
	v_mul_f32_e32 v207, v5, v171
	v_mul_f32_e32 v223, v7, v169
	v_fmac_f32_e32 v207, v4, v170
	v_fmac_f32_e32 v223, v6, v168
	v_add_f32_e32 v206, 0, v206
	v_add_f32_e32 v207, v207, v223
	v_add_f32_e32 v206, v207, v206
	v_mul_f32_e32 v207, v9, v167
	v_mul_f32_e32 v223, v11, v165
	v_fmac_f32_e32 v207, v8, v166
	v_fmac_f32_e32 v223, v10, v164
	s_waitcnt vmcnt(6)
	v_pk_fma_f32 v[160:161], v[202:203], v[160:161], v[142:143]
	v_pk_fma_f32 v[162:163], v[204:205], v[226:227], v[140:141]
	v_add_f32_e32 v207, v207, v223
	v_add_f32_e32 v206, v207, v206
	v_mul_f32_e32 v207, v13, v163
	v_mul_f32_e32 v223, v15, v161
	v_fmac_f32_e32 v207, v12, v162
	v_fmac_f32_e32 v223, v14, v160
	v_add_f32_e32 v207, v207, v223
	v_mul_f32_e32 v223, v175, v17
	v_mul_f32_e32 v226, v173, v19
	v_fmac_f32_e32 v223, v174, v16
	v_fmac_f32_e32 v226, v172, v18
	v_add_f32_e32 v223, v223, v226
	v_mul_f32_e32 v226, v171, v21
	v_mul_f32_e32 v227, v169, v23
	v_fmac_f32_e32 v226, v170, v20
	v_fmac_f32_e32 v227, v168, v22
	v_add_f32_e32 v223, 0, v223
	v_add_f32_e32 v226, v226, v227
	v_add_f32_e32 v223, v223, v226
	v_mul_f32_e32 v226, v167, v25
	v_mul_f32_e32 v227, v165, v27
	v_fmac_f32_e32 v226, v166, v24
	v_fmac_f32_e32 v227, v164, v26
	v_add_f32_e32 v226, v226, v227
	v_add_f32_e32 v223, v223, v226
	v_mul_f32_e32 v226, v163, v29
	v_mul_f32_e32 v227, v161, v31
	v_fmac_f32_e32 v226, v162, v28
	v_fmac_f32_e32 v227, v160, v30
	v_add_f32_e32 v226, v226, v227
	v_add_f32_e32 v206, v207, v206
	v_add_f32_e32 v223, v223, v226
	ds_bpermute_b32 v207, v209, v206
	ds_bpermute_b32 v226, v209, v223
	global_store_dwordx2 v[186:187], v[224:225], off
	v_bfe_u32 v224, v162, 16, 1
	v_add3_u32 v224, v162, v224, s42
	s_waitcnt lgkmcnt(1)
	v_add_f32_e32 v206, v206, v207
	s_waitcnt lgkmcnt(0)
	v_add_f32_e32 v223, v223, v226
	ds_bpermute_b32 v207, v211, v206
	ds_bpermute_b32 v225, v211, v223
	v_bfe_u32 v226, v163, 16, 1
	v_lshrrev_b32_e32 v224, 16, v224
	v_add3_u32 v226, v163, v226, s42
	s_waitcnt lgkmcnt(1)
	v_add_f32_e32 v206, v206, v207
	s_waitcnt lgkmcnt(0)
	v_add_f32_e32 v223, v223, v225
	ds_bpermute_b32 v207, v212, v206
	ds_bpermute_b32 v225, v212, v223
	v_mul_f32_e32 v228, v169, v39
	v_fmac_f32_e32 v228, v168, v38
	v_mul_f32_e32 v229, v173, v51
	s_waitcnt lgkmcnt(1)
	v_add_f32_e32 v207, v206, v207
	s_waitcnt lgkmcnt(0)
	v_add_f32_e32 v223, v223, v225
	ds_bpermute_b32 v227, v213, v207
	ds_bpermute_b32 v225, v213, v223
	v_and_or_b32 v206, v226, s43, v224
	v_bfe_u32 v224, v160, 16, 1
	v_fmac_f32_e32 v229, v172, v50
	s_waitcnt lgkmcnt(1)
	v_add_f32_e32 v207, v207, v227
	s_waitcnt lgkmcnt(0)
	v_add_f32_e32 v225, v223, v225
	ds_bpermute_b32 v226, v214, v207
	ds_bpermute_b32 v227, v214, v225
	v_add3_u32 v223, v160, v224, s42
	v_lshrrev_b32_e32 v233, 16, v223
	v_mul_f32_e32 v230, v169, v55
	s_waitcnt lgkmcnt(1)
	v_add_f32_e32 v223, v207, v226
	s_waitcnt lgkmcnt(0)
	v_add_f32_e32 v225, v225, v227
	v_mul_f32_e32 v207, v175, v33
	v_mul_f32_e32 v227, v173, v35
	v_fmac_f32_e32 v207, v174, v32
	v_fmac_f32_e32 v227, v172, v34
	v_add_f32_e32 v207, v207, v227
	v_mul_f32_e32 v227, v171, v37
	v_fmac_f32_e32 v227, v170, v36
	v_add_f32_e32 v207, 0, v207
	v_add_f32_e32 v227, v227, v228
	v_add_f32_e32 v207, v207, v227
	v_mul_f32_e32 v227, v167, v41
	v_mul_f32_e32 v228, v165, v43
	v_fmac_f32_e32 v227, v166, v40
	v_fmac_f32_e32 v228, v164, v42
	v_add_f32_e32 v227, v227, v228
	v_add_f32_e32 v207, v207, v227
	v_mul_f32_e32 v227, v163, v45
	v_mul_f32_e32 v228, v161, v47
	v_fmac_f32_e32 v227, v162, v44
	v_fmac_f32_e32 v228, v160, v46
	v_add_f32_e32 v227, v227, v228
	v_mul_f32_e32 v228, v175, v49
	v_fmac_f32_e32 v228, v174, v48
	v_add_f32_e32 v228, v228, v229
	v_mul_f32_e32 v229, v171, v53
	v_fmac_f32_e32 v229, v170, v52
	v_fmac_f32_e32 v230, v168, v54
	v_add_f32_e32 v228, 0, v228
	v_add_f32_e32 v229, v229, v230
	v_add_f32_e32 v228, v228, v229
	v_mul_f32_e32 v229, v167, v57
	v_mul_f32_e32 v230, v165, v59
	v_fmac_f32_e32 v229, v166, v56
	v_fmac_f32_e32 v230, v164, v58
	v_add_f32_e32 v229, v229, v230
	v_add_f32_e32 v228, v228, v229
	v_mul_f32_e32 v229, v163, v61
	v_mul_f32_e32 v230, v161, v63
	v_fmac_f32_e32 v229, v162, v60
	v_fmac_f32_e32 v230, v160, v62
	v_add_f32_e32 v229, v229, v230
	v_mul_f32_e32 v230, v175, v65
	v_mul_f32_e32 v231, v173, v67
	v_fmac_f32_e32 v230, v174, v64
	v_fmac_f32_e32 v231, v172, v66
	v_add_f32_e32 v230, v230, v231
	v_mul_f32_e32 v231, v171, v69
	v_mul_f32_e32 v232, v169, v71
	v_fmac_f32_e32 v231, v170, v68
	v_fmac_f32_e32 v232, v168, v70
	v_add_f32_e32 v230, 0, v230
	v_add_f32_e32 v231, v231, v232
	v_add_f32_e32 v230, v230, v231
	v_mul_f32_e32 v231, v167, v73
	v_mul_f32_e32 v232, v165, v75
	v_fmac_f32_e32 v231, v166, v72
	v_fmac_f32_e32 v232, v164, v74
	v_add_f32_e32 v231, v231, v232
	v_add_f32_e32 v230, v230, v231
	v_mul_f32_e32 v231, v163, v77
	v_mul_f32_e32 v232, v161, v79
	v_fmac_f32_e32 v231, v162, v76
	v_fmac_f32_e32 v232, v160, v78
	v_add_f32_e32 v231, v231, v232
	v_add_f32_e32 v207, v207, v227
	v_add_f32_e32 v230, v230, v231
	ds_bpermute_b32 v227, v209, v207
	ds_bpermute_b32 v231, v209, v230
	v_mul_f32_e32 v235, v169, v87
	v_fmac_f32_e32 v235, v168, v86
	v_mul_f32_e32 v236, v173, v99
	s_waitcnt lgkmcnt(1)
	v_add_f32_e32 v207, v207, v227
	s_waitcnt lgkmcnt(0)
	v_add_f32_e32 v230, v230, v231
	ds_bpermute_b32 v227, v211, v207
	ds_bpermute_b32 v231, v211, v230
	v_fmac_f32_e32 v236, v172, v98
	v_mul_f32_e32 v237, v169, v103
	v_fmac_f32_e32 v237, v168, v102
	s_waitcnt lgkmcnt(1)
	v_add_f32_e32 v207, v207, v227
	s_waitcnt lgkmcnt(0)
	v_add_f32_e32 v230, v230, v231
	ds_bpermute_b32 v227, v212, v207
	ds_bpermute_b32 v231, v212, v230
	v_mul_f32_e32 v169, v169, v119
	v_fmac_f32_e32 v169, v168, v118
	v_add_f32_e32 v228, v228, v229
	s_waitcnt lgkmcnt(1)
	v_add_f32_e32 v207, v207, v227
	s_waitcnt lgkmcnt(0)
	v_add_f32_e32 v230, v230, v231
	ds_bpermute_b32 v227, v213, v207
	ds_bpermute_b32 v231, v213, v230
	ds_bpermute_b32 v229, v209, v228
	ds_bpermute_b32 v224, v215, v223
	ds_bpermute_b32 v226, v215, v225
	s_waitcnt lgkmcnt(4)
	v_add_f32_e32 v207, v207, v227
	s_waitcnt lgkmcnt(3)
	v_add_f32_e32 v231, v230, v231
	ds_bpermute_b32 v227, v214, v207
	ds_bpermute_b32 v234, v214, v231
	s_waitcnt lgkmcnt(4)
	v_add_f32_e32 v228, v228, v229
	ds_bpermute_b32 v229, v211, v228
	s_waitcnt lgkmcnt(2)
	v_add_f32_e32 v227, v207, v227
	s_waitcnt lgkmcnt(1)
	v_add_f32_e32 v231, v231, v234
	v_mul_f32_e32 v207, v175, v81
	v_mul_f32_e32 v234, v173, v83
	v_fmac_f32_e32 v207, v174, v80
	v_fmac_f32_e32 v234, v172, v82
	v_add_f32_e32 v207, v207, v234
	v_mul_f32_e32 v234, v171, v85
	v_fmac_f32_e32 v234, v170, v84
	v_add_f32_e32 v207, 0, v207
	v_add_f32_e32 v234, v234, v235
	v_add_f32_e32 v207, v207, v234
	v_mul_f32_e32 v234, v167, v89
	v_mul_f32_e32 v235, v165, v91
	v_fmac_f32_e32 v234, v166, v88
	v_fmac_f32_e32 v235, v164, v90
	v_add_f32_e32 v234, v234, v235
	v_add_f32_e32 v207, v207, v234
	v_mul_f32_e32 v234, v163, v93
	v_mul_f32_e32 v235, v161, v95
	v_fmac_f32_e32 v234, v162, v92
	v_fmac_f32_e32 v235, v160, v94
	v_add_f32_e32 v234, v234, v235
	v_mul_f32_e32 v235, v175, v97
	v_fmac_f32_e32 v235, v174, v96
	v_add_f32_e32 v235, v235, v236
	v_mul_f32_e32 v236, v171, v101
	v_fmac_f32_e32 v236, v170, v100
	v_add_f32_e32 v235, 0, v235
	v_add_f32_e32 v236, v236, v237
	v_add_f32_e32 v235, v235, v236
	v_mul_f32_e32 v236, v167, v105
	v_mul_f32_e32 v237, v165, v107
	v_fmac_f32_e32 v236, v166, v104
	v_fmac_f32_e32 v237, v164, v106
	v_mul_f32_e32 v175, v175, v113
	v_mul_f32_e32 v173, v173, v115
	v_add_f32_e32 v236, v236, v237
	v_fmac_f32_e32 v175, v174, v112
	v_fmac_f32_e32 v173, v172, v114
	v_mul_f32_e32 v171, v171, v117
	v_add_f32_e32 v235, v235, v236
	v_mul_f32_e32 v236, v163, v109
	v_add_f32_e32 v172, v175, v173
	v_fmac_f32_e32 v171, v170, v116
	v_mul_f32_e32 v167, v167, v121
	v_mul_f32_e32 v165, v165, v123
	v_mul_f32_e32 v163, v163, v125
	v_fmac_f32_e32 v236, v162, v108
	v_mul_f32_e32 v237, v161, v111
	v_add_f32_e32 v172, 0, v172
	v_add_f32_e32 v168, v171, v169
	v_fmac_f32_e32 v167, v166, v120
	v_fmac_f32_e32 v165, v164, v122
	v_fmac_f32_e32 v163, v162, v124
	v_mul_f32_e32 v162, v161, v127
	v_fmac_f32_e32 v237, v160, v110
	v_add_f32_e32 v168, v172, v168
	v_add_f32_e32 v164, v167, v165
	v_fmac_f32_e32 v162, v160, v126
	v_add_f32_e32 v236, v236, v237
	v_add_f32_e32 v164, v168, v164
	v_add_f32_e32 v160, v163, v162
	v_add_f32_e32 v207, v207, v234
	v_add_f32_e32 v235, v235, v236
	v_add_f32_e32 v160, v164, v160
	ds_bpermute_b32 v234, v209, v207
	ds_bpermute_b32 v236, v209, v235
	ds_bpermute_b32 v162, v209, v160
	s_waitcnt lgkmcnt(3)
	v_add_f32_e32 v228, v228, v229
	ds_bpermute_b32 v229, v212, v228
	s_waitcnt lgkmcnt(3)
	v_add_f32_e32 v163, v207, v234
	s_waitcnt lgkmcnt(2)
	v_add_f32_e32 v165, v235, v236
	s_waitcnt lgkmcnt(1)
	v_add_f32_e32 v160, v160, v162
	ds_bpermute_b32 v164, v211, v163
	ds_bpermute_b32 v166, v211, v165
	ds_bpermute_b32 v162, v211, v160
	s_waitcnt lgkmcnt(3)
	v_add_f32_e32 v228, v228, v229
	ds_bpermute_b32 v229, v213, v228
	s_waitcnt lgkmcnt(3)
	v_add_f32_e32 v163, v163, v164
	s_waitcnt lgkmcnt(2)
	v_add_f32_e32 v165, v165, v166
	s_waitcnt lgkmcnt(1)
	v_add_f32_e32 v160, v160, v162
	ds_bpermute_b32 v164, v212, v163
	ds_bpermute_b32 v166, v212, v165
	ds_bpermute_b32 v162, v212, v160
	s_waitcnt lgkmcnt(3)
	v_add_f32_e32 v229, v228, v229
	ds_bpermute_b32 v232, v214, v229
	s_waitcnt lgkmcnt(3)
	v_add_f32_e32 v163, v163, v164
	s_waitcnt lgkmcnt(2)
	v_add_f32_e32 v165, v165, v166
	s_waitcnt lgkmcnt(1)
	v_add_f32_e32 v160, v160, v162
	ds_bpermute_b32 v164, v213, v163
	ds_bpermute_b32 v166, v213, v165
	ds_bpermute_b32 v162, v213, v160
	s_waitcnt lgkmcnt(3)
	v_add_f32_e32 v229, v229, v232
	ds_bpermute_b32 v228, v215, v227
	s_waitcnt lgkmcnt(3)
	v_add_f32_e32 v163, v163, v164
	s_waitcnt lgkmcnt(2)
	v_add_f32_e32 v165, v165, v166
	s_waitcnt lgkmcnt(1)
	v_add_f32_e32 v167, v160, v162
	ds_bpermute_b32 v164, v214, v163
	ds_bpermute_b32 v166, v214, v165
	ds_bpermute_b32 v168, v214, v167
	ds_bpermute_b32 v230, v215, v229
	ds_bpermute_b32 v232, v215, v231
	s_waitcnt lgkmcnt(4)
	v_add_f32_e32 v160, v163, v164
	s_waitcnt lgkmcnt(3)
	v_add_f32_e32 v163, v165, v166
	s_waitcnt lgkmcnt(2)
	v_add_f32_e32 v165, v167, v168
	ds_bpermute_b32 v162, v215, v160
	ds_bpermute_b32 v164, v215, v163
	ds_bpermute_b32 v166, v215, v165
	v_bfe_u32 v167, v161, 16, 1
	v_add3_u32 v161, v161, v167, s42
	v_and_or_b32 v207, v161, s43, v233
	global_store_dwordx2 v[186:187], v[206:207], off offset:512
	s_and_saveexec_b64 s[36:37], s[4:5]
	s_cbranch_execz .LBB0_401
	v_mov_b32_e32 v161, v255
	v_add_f32_e32 v167, v225, v226
	v_add_f32_e32 v168, v223, v224
	s_waitcnt lgkmcnt(0)
	v_add_f32_e32 v165, v165, v166
	v_add_f32_e32 v166, v227, v228
	v_cndmask_b32_e64 v167, v168, v167, s[18:19]
	v_add_f32_e32 v163, v163, v164
	v_add_f32_e32 v164, v229, v230
	v_cndmask_b32_e64 v166, v167, v166, s[16:17]
	v_add_f32_e32 v160, v160, v162
	v_add_f32_e32 v162, v231, v232
	v_cndmask_b32_e64 v164, v166, v164, s[14:15]
	v_cndmask_b32_e64 v162, v164, v162, s[12:13]
	v_cndmask_b32_e64 v160, v162, v160, s[10:11]
	v_cndmask_b32_e64 v160, v160, v163, s[8:9]
	v_cndmask_b32_e64 v160, v160, v165, s[6:7]
	v_add_f32_e32 v160, v160, v161
	v_mul_f32_e64 v161, |v160|, s48
	v_exp_f32_e32 v161, v161
	v_min_f32_e32 v160, 0, v160
	v_add_f32_e32 v161, 1.0, v161
	v_cmp_gt_f32_e32 vcc, s49, v161
	s_nop 1
	v_cndmask_b32_e64 v162, 0, 32, vcc
	v_ldexp_f32 v161, v161, v162
	v_log_f32_e32 v161, v161
	s_nop 0
	v_mul_f32_e32 v162, 0x3f317217, v161
	v_fma_f32 v162, v161, s52, -v162
	v_fmac_f32_e32 v162, 0x3377d1cf, v161
	v_fmac_f32_e32 v162, 0x3f317217, v161
	v_cmp_lt_f32_e64 s[0:1], |v161|, s53
	s_nop 1
	v_cndmask_b32_e64 v161, v161, v162, s[0:1]
	v_cndmask_b32_e32 v162, 0, v222, vcc
	v_sub_f32_e32 v161, v161, v162
	v_sub_f32_e32 v160, v160, v161
	global_store_dword v[188:189], v160, off
	s_branch .LBB0_401
